# top-k radix select: the largest key of the query is found first and candidate thresholds above it are rejected without a counting pass (same decisions, fewer passes)
# speedup vs baseline: 1.0177x; 1.0028x over previous
; #define TK_GRP(g) { const int c0 = __popcll(__ballot(u[4 * (g)] >= cand)), c1 = __popcll(__ballot(u[4 * (g) + 1] >= cand)), c2 = __popcll(__ballot(u[4 * (g) + 2] >= cand)), c3 = __popcll(__ballot(u[4 * (g) + 3] >= cand)); cnt += (c0 + c1) + (c2 + c3); }
; __device__ __forceinline__ void indexer_unit(const Args& a, LAS unsigned char* lds, LAS unsigned long long* maskl, int b, int qblk, int wave, int lane) {
;     ...
;             for (int g = 0; g < 8; ++g) if (4 * g < nr) {
; #pragma unroll
;                 for (int k4 = 0; k4 < 4; ++k4) { const int r = 4 * g + k4; const int idx = 64 * r + lane; const unsigned bits = __builtin_bit_cast(unsigned, sc[q * 2048 + idx]);
;                     const unsigned k = bits ^ (((unsigned)((int)bits >> 31)) | 0x80000000u); u[r] = idx < n ? k : 0u; } }
;             unsigned T = 0u; bool exact = false; const int ng = (nr + 3) >> 2;
; #pragma unroll 1
;     ...
;                 const unsigned cand = T | (1u << bit); int cnt = 0;
;     ...
;                 switch (ng) {
;                     case 8: TK_GRP(7) [[fallthrough]];
;                     case 7: TK_GRP(6) [[fallthrough]];
;                     case 6: TK_GRP(5) [[fallthrough]];
;                     case 5: TK_GRP(4) [[fallthrough]];
;                     case 4: TK_GRP(3) [[fallthrough]];
;                     case 3: TK_GRP(2) [[fallthrough]];
;                     case 2: TK_GRP(1) [[fallthrough]];
;                     default: TK_GRP(0)
;                 }
;     ...
;                 if (cnt >= 256) { T = cand; if (cnt == 256) { exact = true; break; } }
;             }
.Ltk_ld_done:
	v_max_u32_e32 v25, v33, v32
	v_max_u32_e32 v25, v34, v25
	v_max_u32_e32 v25, v35, v25
	v_max_u32_e32 v25, v36, v25
	v_max_u32_e32 v25, v37, v25
	v_max_u32_e32 v25, v38, v25
	v_max_u32_e32 v25, v39, v25
	s_cmp_lt_u32 s21, 2
	s_cbranch_scc1 .Ltk_mx_done
	v_max_u32_e32 v25, v40, v25
	v_max_u32_e32 v25, v41, v25
	v_max_u32_e32 v25, v42, v25
	v_max_u32_e32 v25, v43, v25
	v_max_u32_e32 v25, v44, v25
	v_max_u32_e32 v25, v45, v25
	v_max_u32_e32 v25, v46, v25
	v_max_u32_e32 v25, v47, v25
	s_cmp_lt_u32 s21, 3
	s_cbranch_scc1 .Ltk_mx_done
	v_max_u32_e32 v25, v48, v25
	v_max_u32_e32 v25, v49, v25
	v_max_u32_e32 v25, v50, v25
	v_max_u32_e32 v25, v51, v25
	v_max_u32_e32 v25, v52, v25
	v_max_u32_e32 v25, v53, v25
	v_max_u32_e32 v25, v54, v25
	v_max_u32_e32 v25, v55, v25
	s_cmp_lt_u32 s21, 4
	s_cbranch_scc1 .Ltk_mx_done
	v_max_u32_e32 v25, v56, v25
	v_max_u32_e32 v25, v57, v25
	v_max_u32_e32 v25, v58, v25
	v_max_u32_e32 v25, v59, v25
	v_max_u32_e32 v25, v60, v25
	v_max_u32_e32 v25, v61, v25
	v_max_u32_e32 v25, v62, v25
	v_max_u32_e32 v25, v63, v25
.Ltk_mx_done:
	s_nop 1
	v_max_u32_dpp v26, v25, v25 quad_perm:[1,0,3,2] row_mask:0xf bank_mask:0xf
	s_nop 1
	v_max_u32_dpp v25, v26, v26 quad_perm:[2,3,0,1] row_mask:0xf bank_mask:0xf
	s_nop 1
	v_max_u32_dpp v26, v25, v25 row_half_mirror row_mask:0xf bank_mask:0xf
	s_nop 1
	v_max_u32_dpp v25, v26, v26 row_mirror row_mask:0xf bank_mask:0xf
	s_nop 1
	v_readlane_b32 s16, v25, 0
	v_readlane_b32 s17, v25, 16
	v_readlane_b32 s22, v25, 32
	v_readlane_b32 s23, v25, 48
	s_max_u32 s18, s16, s17
	s_max_u32 s22, s22, s23
	s_max_u32 s18, s18, s22
	s_mov_b32 s10, 0
	s_mov_b32 s11, 31
.Ltk_bit:
	s_lshl_b32 s12, 1, s11
	s_or_b32 s13, s10, s12
	s_cmp_gt_u32 s13, s18
	s_cbranch_scc1 .Ltk_nxt
	v_mov_b32_e32 v24, 0
	v_cmp_le_u32_e64 s[24:25], s13, v32
	v_cmp_le_u32_e64 s[26:27], s13, v33
	v_cmp_le_u32_e64 s[28:29], s13, v34
	v_cmp_le_u32_e64 s[30:31], s13, v35
	v_cmp_le_u32_e64 s[34:35], s13, v36
	v_cmp_le_u32_e64 s[36:37], s13, v37
	v_cmp_le_u32_e64 s[38:39], s13, v38
	v_cmp_le_u32_e64 s[40:41], s13, v39
	s_bcnt1_i32_b64 s42, s[24:25]
	s_bcnt1_i32_b64 s43, s[26:27]
	s_bcnt1_i32_b64 s44, s[28:29]
	s_bcnt1_i32_b64 s45, s[30:31]
	s_bcnt1_i32_b64 s46, s[34:35]
	s_bcnt1_i32_b64 s47, s[36:37]
	s_bcnt1_i32_b64 s48, s[38:39]
	s_bcnt1_i32_b64 s49, s[40:41]
	s_add_i32 s14, s42, s43
	v_add_u32_e32 v24, s44, v24
	v_add_u32_e32 v24, s45, v24
	v_add_u32_e32 v24, s46, v24
	v_add_u32_e32 v24, s47, v24
	v_add_u32_e32 v24, s48, v24
	v_add_u32_e32 v24, s49, v24
	s_cmp_lt_u32 s21, 2
	s_cbranch_scc1 .Ltk_dec
	v_cmp_le_u32_e64 s[24:25], s13, v40
	v_cmp_le_u32_e64 s[26:27], s13, v41
	v_cmp_le_u32_e64 s[28:29], s13, v42
	v_cmp_le_u32_e64 s[30:31], s13, v43
	v_cmp_le_u32_e64 s[34:35], s13, v44
	v_cmp_le_u32_e64 s[36:37], s13, v45
	v_cmp_le_u32_e64 s[38:39], s13, v46
	v_cmp_le_u32_e64 s[40:41], s13, v47
	s_bcnt1_i32_b64 s42, s[24:25]
	s_bcnt1_i32_b64 s43, s[26:27]
	s_bcnt1_i32_b64 s44, s[28:29]
	s_bcnt1_i32_b64 s45, s[30:31]
	s_bcnt1_i32_b64 s46, s[34:35]
	s_bcnt1_i32_b64 s47, s[36:37]
	s_bcnt1_i32_b64 s48, s[38:39]
	s_bcnt1_i32_b64 s49, s[40:41]
	s_add_i32 s14, s14, s42
	s_add_i32 s14, s14, s43
	v_add_u32_e32 v24, s44, v24
	v_add_u32_e32 v24, s45, v24
	v_add_u32_e32 v24, s46, v24
	v_add_u32_e32 v24, s47, v24
	v_add_u32_e32 v24, s48, v24
	v_add_u32_e32 v24, s49, v24
	s_cmp_lt_u32 s21, 3
	s_cbranch_scc1 .Ltk_dec
	v_cmp_le_u32_e64 s[24:25], s13, v48
	v_cmp_le_u32_e64 s[26:27], s13, v49
	v_cmp_le_u32_e64 s[28:29], s13, v50
	v_cmp_le_u32_e64 s[30:31], s13, v51
	v_cmp_le_u32_e64 s[34:35], s13, v52
	v_cmp_le_u32_e64 s[36:37], s13, v53
	v_cmp_le_u32_e64 s[38:39], s13, v54
	v_cmp_le_u32_e64 s[40:41], s13, v55
	s_bcnt1_i32_b64 s42, s[24:25]
	s_bcnt1_i32_b64 s43, s[26:27]
	s_bcnt1_i32_b64 s44, s[28:29]
	s_bcnt1_i32_b64 s45, s[30:31]
	s_bcnt1_i32_b64 s46, s[34:35]
	s_bcnt1_i32_b64 s47, s[36:37]
	s_bcnt1_i32_b64 s48, s[38:39]
	s_bcnt1_i32_b64 s49, s[40:41]
	s_add_i32 s14, s14, s42
	s_add_i32 s14, s14, s43
	v_add_u32_e32 v24, s44, v24
	v_add_u32_e32 v24, s45, v24
	v_add_u32_e32 v24, s46, v24
	v_add_u32_e32 v24, s47, v24
	v_add_u32_e32 v24, s48, v24
	v_add_u32_e32 v24, s49, v24
	s_cmp_lt_u32 s21, 4
	s_cbranch_scc1 .Ltk_dec
	v_cmp_le_u32_e64 s[24:25], s13, v56
	v_cmp_le_u32_e64 s[26:27], s13, v57
	v_cmp_le_u32_e64 s[28:29], s13, v58
	v_cmp_le_u32_e64 s[30:31], s13, v59
	v_cmp_le_u32_e64 s[34:35], s13, v60
	v_cmp_le_u32_e64 s[36:37], s13, v61
	v_cmp_le_u32_e64 s[38:39], s13, v62
	v_cmp_le_u32_e64 s[40:41], s13, v63
	s_bcnt1_i32_b64 s42, s[24:25]
	s_bcnt1_i32_b64 s43, s[26:27]
	s_bcnt1_i32_b64 s44, s[28:29]
	s_bcnt1_i32_b64 s45, s[30:31]
	s_bcnt1_i32_b64 s46, s[34:35]
	s_bcnt1_i32_b64 s47, s[36:37]
	s_bcnt1_i32_b64 s48, s[38:39]
	s_bcnt1_i32_b64 s49, s[40:41]
	s_add_i32 s14, s14, s42
	s_add_i32 s14, s14, s43
	v_add_u32_e32 v24, s44, v24
	v_add_u32_e32 v24, s45, v24
	v_add_u32_e32 v24, s46, v24
	v_add_u32_e32 v24, s47, v24
	v_add_u32_e32 v24, s48, v24
	v_add_u32_e32 v24, s49, v24
